# v36 plus static s_setprio 1 for waves 4-7 in the three big GEMM phases (per-iteration priority toggles removed)
# baseline (speedup 1.0000x reference)
; template <int MI, int NJ> ...
;     ...
;   for (int kt = 0; kt < nk; ++kt) {
;     const int buf = kt & 1;
;     {
;       G8STORE(buf ^ 1);
;       const u16* ga_ = (kt + 2 < nk) ? Ag + (kt + 2) * 64 : Ag + nAoff;
;       const u16* gb_ = (kt + 2 < nk) ? Bg + (kt + 2) * 64 : Bg + nBoff;
;       G8LOADP(ga_, gb_);
;     }
;     __builtin_amdgcn_sched_barrier(0);
;     __builtin_amdgcn_s_setprio(1);
;     const u16* a = ra_ + buf * AROWS * 64;
;     const u16* b = rb_ + buf * BROWS * 64;
; #pragma unroll
;     for (int ks = 0; ks < 2; ++ks) {
;       const u16* a_ = ks ? a + dsw : a;
;       const u16* b_ = ks ? b + dsw : b;
;       bf16x8 bfr[NJ];
; #pragma unroll
;       for (int j = 0; j < NJ; ++j) bfr[j] = *(const bf16x8*)(b_ + j * 16 * 64);
; #pragma unroll
;       for (int ih = 0; ih < MI / 4; ++ih) {
;         bf16x8 af[4];
; #pragma unroll
;         for (int i = 0; i < 4; ++i) af[i] = *(const bf16x8*)(a_ + (ih * 4 + i) * 16 * 64);
; #pragma unroll
;         for (int i = 0; i < 4; ++i)
; #pragma unroll
;           for (int j = 0; j < NJ; ++j) acc[ih * 4 + i][j] = mfma16(af[i], bfr[j], acc[ih * 4 + i][j]);
;       }
;     }
;     __builtin_amdgcn_s_setprio(0);
;     __builtin_amdgcn_sched_barrier(0);
;     __syncthreads();
;   }
.LBB0_470:
	s_waitcnt lgkmcnt(6)
	v_mfma_f32_16x16x32_bf16 v[158:161], v[166:169], v[162:165], v[158:161]
	s_waitcnt lgkmcnt(5)
	v_mfma_f32_16x16x32_bf16 v[154:157], v[170:173], v[162:165], v[154:157]
	s_waitcnt lgkmcnt(4)
	v_mfma_f32_16x16x32_bf16 v[150:153], v[192:195], v[162:165], v[150:153]
	s_waitcnt lgkmcnt(3)
	v_mfma_f32_16x16x32_bf16 v[146:149], v[196:199], v[162:165], v[146:149]
	ds_read_b128 v[162:165], v0 offset:8192
	s_waitcnt lgkmcnt(3)
	v_mfma_f32_16x16x32_bf16 v[142:145], v[166:169], v[204:207], v[142:145]
	v_mfma_f32_16x16x32_bf16 v[138:141], v[170:173], v[204:207], v[138:141]
	v_mfma_f32_16x16x32_bf16 v[134:137], v[192:195], v[204:207], v[134:137]
	v_mfma_f32_16x16x32_bf16 v[130:133], v[196:199], v[204:207], v[130:133]
	ds_read_b128 v[204:207], v0 offset:10240
	s_waitcnt lgkmcnt(3)
	v_mfma_f32_16x16x32_bf16 v[126:129], v[166:169], v[208:211], v[126:129]
	v_mfma_f32_16x16x32_bf16 v[122:125], v[170:173], v[208:211], v[122:125]
	v_mfma_f32_16x16x32_bf16 v[118:121], v[192:195], v[208:211], v[118:121]
	v_mfma_f32_16x16x32_bf16 v[114:117], v[196:199], v[208:211], v[114:117]
	ds_read_b128 v[208:211], v0 offset:12288
	ds_read_b128 v[212:215], v191
	ds_read_b128 v[216:219], v191 offset:2048
	s_waitcnt lgkmcnt(5)
	v_mfma_f32_16x16x32_bf16 v[110:113], v[166:169], v[238:241], v[110:113]
	v_mfma_f32_16x16x32_bf16 v[106:109], v[170:173], v[238:241], v[106:109]
	v_mfma_f32_16x16x32_bf16 v[102:105], v[192:195], v[238:241], v[102:105]
	v_mfma_f32_16x16x32_bf16 v[98:101], v[196:199], v[238:241], v[98:101]
	ds_read_b128 v[238:241], v0 offset:14336
	ds_read_b128 v[220:223], v191 offset:4096
	ds_read_b128 v[224:227], v191 offset:6144
	s_waitcnt lgkmcnt(7)
	v_mfma_f32_16x16x32_bf16 v[94:97], v[166:169], v[162:165], v[94:97]
	v_mfma_f32_16x16x32_bf16 v[90:93], v[170:173], v[162:165], v[90:93]
	v_mfma_f32_16x16x32_bf16 v[86:89], v[192:195], v[162:165], v[86:89]
	v_mfma_f32_16x16x32_bf16 v[82:85], v[196:199], v[162:165], v[82:85]
	v_add_u32_e32 v0, v0, v190
	ds_read_b128 v[162:165], v0
	s_waitcnt vmcnt(7)
	ds_write_b128 v228, v[10:13]
	global_load_dwordx4 v[10:13], v234, s[52:53]
	s_waitcnt lgkmcnt(8)
	v_mfma_f32_16x16x32_bf16 v[78:81], v[166:169], v[204:207], v[78:81]
	v_mfma_f32_16x16x32_bf16 v[74:77], v[170:173], v[204:207], v[74:77]
	v_mfma_f32_16x16x32_bf16 v[70:73], v[192:195], v[204:207], v[70:73]
	v_mfma_f32_16x16x32_bf16 v[66:69], v[196:199], v[204:207], v[66:69]
	ds_read_b128 v[204:207], v0 offset:2048
	s_waitcnt vmcnt(7)
	ds_write_b128 v228, v[2:5] offset:8192
	global_load_dwordx4 v[2:5], v235, s[52:53]
	s_waitcnt lgkmcnt(9)
	v_mfma_f32_16x16x32_bf16 v[62:65], v[166:169], v[208:211], v[62:65]
	v_mfma_f32_16x16x32_bf16 v[58:61], v[170:173], v[208:211], v[58:61]
	v_mfma_f32_16x16x32_bf16 v[54:57], v[192:195], v[208:211], v[54:57]
	v_mfma_f32_16x16x32_bf16 v[50:53], v[196:199], v[208:211], v[50:53]
	ds_read_b128 v[208:211], v0 offset:4096
	s_waitcnt vmcnt(7)
	ds_write_b128 v228, v[6:9] offset:16384
	global_load_dwordx4 v[6:9], v236, s[52:53]
	s_waitcnt lgkmcnt(8)
	v_mfma_f32_16x16x32_bf16 v[46:49], v[166:169], v[238:241], v[46:49]
	v_mfma_f32_16x16x32_bf16 v[42:45], v[170:173], v[238:241], v[42:45]
	v_mfma_f32_16x16x32_bf16 v[38:41], v[192:195], v[238:241], v[38:41]
	v_mfma_f32_16x16x32_bf16 v[34:37], v[196:199], v[238:241], v[34:37]
	ds_read_b128 v[238:241], v0 offset:6144
	s_waitcnt vmcnt(7)
	ds_write_b128 v228, v[18:21] offset:24576
	global_load_dwordx4 v[18:21], v237, s[52:53]
	s_waitcnt lgkmcnt(7)
	v_mfma_f32_16x16x32_bf16 v[158:161], v[212:215], v[162:165], v[158:161]
	v_mfma_f32_16x16x32_bf16 v[154:157], v[216:219], v[162:165], v[154:157]
	v_mfma_f32_16x16x32_bf16 v[150:153], v[220:223], v[162:165], v[150:153]
	v_mfma_f32_16x16x32_bf16 v[146:149], v[224:227], v[162:165], v[146:149]
	ds_read_b128 v[162:165], v0 offset:8192
	s_waitcnt vmcnt(7)
	ds_write_b128 v229, v[14:17]
	global_load_dwordx4 v[14:17], v234, s[66:67]
	s_waitcnt lgkmcnt(7)
	v_mfma_f32_16x16x32_bf16 v[142:145], v[212:215], v[204:207], v[142:145]
	v_mfma_f32_16x16x32_bf16 v[138:141], v[216:219], v[204:207], v[138:141]
	v_mfma_f32_16x16x32_bf16 v[134:137], v[220:223], v[204:207], v[134:137]
	v_mfma_f32_16x16x32_bf16 v[130:133], v[224:227], v[204:207], v[130:133]
	ds_read_b128 v[204:207], v0 offset:10240
	s_waitcnt vmcnt(7)
	ds_write_b128 v229, v[22:25] offset:8192
	global_load_dwordx4 v[22:25], v235, s[66:67]
	s_waitcnt lgkmcnt(7)
	v_mfma_f32_16x16x32_bf16 v[126:129], v[212:215], v[208:211], v[126:129]
	v_mfma_f32_16x16x32_bf16 v[122:125], v[216:219], v[208:211], v[122:125]
	v_mfma_f32_16x16x32_bf16 v[118:121], v[220:223], v[208:211], v[118:121]
	v_mfma_f32_16x16x32_bf16 v[114:117], v[224:227], v[208:211], v[114:117]
	ds_read_b128 v[208:211], v0 offset:12288
	s_waitcnt vmcnt(7)
	ds_write_b128 v229, v[26:29] offset:16384
	global_load_dwordx4 v[26:29], v236, s[66:67]
	s_waitcnt lgkmcnt(7)
	v_mfma_f32_16x16x32_bf16 v[110:113], v[212:215], v[238:241], v[110:113]
	v_mfma_f32_16x16x32_bf16 v[106:109], v[216:219], v[238:241], v[106:109]
	v_mfma_f32_16x16x32_bf16 v[102:105], v[220:223], v[238:241], v[102:105]
	v_mfma_f32_16x16x32_bf16 v[98:101], v[224:227], v[238:241], v[98:101]
	ds_read_b128 v[238:241], v0 offset:14336
	s_waitcnt vmcnt(7)
	ds_write_b128 v229, v[30:33] offset:24576
	global_load_dwordx4 v[30:33], v237, s[66:67]
	s_waitcnt lgkmcnt(7)
	v_mfma_f32_16x16x32_bf16 v[94:97], v[212:215], v[162:165], v[94:97]
	v_mfma_f32_16x16x32_bf16 v[90:93], v[216:219], v[162:165], v[90:93]
	v_mfma_f32_16x16x32_bf16 v[86:89], v[220:223], v[162:165], v[86:89]
	v_mfma_f32_16x16x32_bf16 v[82:85], v[224:227], v[162:165], v[82:85]
	s_waitcnt lgkmcnt(0)
	s_barrier
; template <int MI, int NJ> ...
;     ...
;   for (int kt = 0; kt < nk; ++kt) {
;     const int buf = kt & 1;
;     {
;       G8STORE(buf ^ 1);
;       const u16* ga_ = (kt + 2 < nk) ? Ag + (kt + 2) * 64 : Ag + nAoff;
;       const u16* gb_ = (kt + 2 < nk) ? Bg + (kt + 2) * 64 : Bg + nBoff;
;       G8LOADP(ga_, gb_);
;     }
;     __builtin_amdgcn_sched_barrier(0);
;     __builtin_amdgcn_s_setprio(1);
;     const u16* a = ra_ + buf * AROWS * 64;
;     const u16* b = rb_ + buf * BROWS * 64;
; #pragma unroll
;     for (int ks = 0; ks < 2; ++ks) {
;       const u16* a_ = ks ? a + dsw : a;
;       const u16* b_ = ks ? b + dsw : b;
;       bf16x8 bfr[NJ];
; #pragma unroll
;       for (int j = 0; j < NJ; ++j) bfr[j] = *(const bf16x8*)(b_ + j * 16 * 64);
; #pragma unroll
;       for (int ih = 0; ih < MI / 4; ++ih) {
;         bf16x8 af[4];
; #pragma unroll
;         for (int i = 0; i < 4; ++i) af[i] = *(const bf16x8*)(a_ + (ih * 4 + i) * 16 * 64);
; #pragma unroll
;         for (int i = 0; i < 4; ++i)
; #pragma unroll
;           for (int j = 0; j < NJ; ++j) acc[ih * 4 + i][j] = mfma16(af[i], bfr[j], acc[ih * 4 + i][j]);
;       }
;     }
;     __builtin_amdgcn_s_setprio(0);
;     __builtin_amdgcn_sched_barrier(0);
;     __syncthreads();
;   }
; __device__ __forceinline__ void phase_gemm_f32(const u16* A, const u16* Bt, int K, u16* out, u16* smem,
;                                                volatile LAS unsigned* vb_) {
;     ...
; #pragma unroll
;     for (int i = 0; i < 8; ++i)
; #pragma unroll
;       for (int j = 0; j < 4; ++j)
; #pragma unroll
;         for (int r = 0; r < 4; ++r)
;           smem[(wm * 128 + i * 16 + (lane >> 4) * 4 + r) * 264 + wn * 64 + j * 16 + (lane & 15)] = f2bf(acc[i][j][r]);
;     __syncthreads();
	s_add_i32 s37, s37, 1
	s_add_u32 s20, s20, 64
	s_addc_u32 s21, s21, 0
	s_addk_i32 s11, 0x4000
	s_and_b32 s38, s11, 0x4000
	s_xor_b32 s39, s38, 0x4000
	s_lshl_b32 s39, s39, 1
	v_add_u32_e32 v228, s39, v185
	v_add_u32_e32 v229, s39, v186
	s_cmp_lt_u32 s37, 14
	s_cselect_b32 s49, s21, s13
	s_cselect_b32 s48, s20, s12
	s_cselect_b32 s51, s21, s47
	s_cselect_b32 s50, s20, s46
	s_lshl_b64 s[48:49], s[48:49], 1
	s_lshl_b64 s[50:51], s[50:51], 1
	s_add_u32 s52, s62, s48
	s_addc_u32 s53, s63, s49
	s_add_u32 s66, s64, s50
	s_addc_u32 s67, s65, s51
	s_lshl_b32 s38, s38, 1
	v_add_u32_e32 v0, s38, v187
	v_add_u32_e32 v191, s38, v188
	ds_read_b128 v[166:169], v191
	ds_read_b128 v[162:165], v0
	ds_read_b128 v[170:173], v191 offset:2048
	ds_read_b128 v[192:195], v191 offset:4096
	ds_read_b128 v[196:199], v191 offset:6144
	v_mfma_f32_16x16x32_bf16 v[78:81], v[212:215], v[204:207], v[78:81]
	v_mfma_f32_16x16x32_bf16 v[74:77], v[216:219], v[204:207], v[74:77]
	v_mfma_f32_16x16x32_bf16 v[70:73], v[220:223], v[204:207], v[70:73]
	v_mfma_f32_16x16x32_bf16 v[66:69], v[224:227], v[204:207], v[66:69]
	ds_read_b128 v[204:207], v0 offset:2048
	v_mfma_f32_16x16x32_bf16 v[62:65], v[212:215], v[208:211], v[62:65]
	v_mfma_f32_16x16x32_bf16 v[58:61], v[216:219], v[208:211], v[58:61]
	v_mfma_f32_16x16x32_bf16 v[54:57], v[220:223], v[208:211], v[54:57]
	v_mfma_f32_16x16x32_bf16 v[50:53], v[224:227], v[208:211], v[50:53]
	ds_read_b128 v[208:211], v0 offset:4096
	v_mfma_f32_16x16x32_bf16 v[46:49], v[212:215], v[238:241], v[46:49]
	v_mfma_f32_16x16x32_bf16 v[42:45], v[216:219], v[238:241], v[42:45]
	v_mfma_f32_16x16x32_bf16 v[38:41], v[220:223], v[238:241], v[38:41]
	v_mfma_f32_16x16x32_bf16 v[34:37], v[224:227], v[238:241], v[34:37]
	ds_read_b128 v[238:241], v0 offset:6144
	v_add_u32_e32 v191, v191, v190
	s_cmpk_lg_i32 s20, 0x480
	s_cbranch_scc1 .LBB0_470
	v_and_b32_e32 v228, 15, v175
	v_bfe_u32 v229, v175, 8, 1
	v_lshl_or_b32 v228, v229, 7, v228
	v_mul_u32_u24_e32 v228, 0x210, v228
	v_bfe_u32 v229, v175, 6, 2
	v_lshl_add_u32 v228, v229, 7, v228
	v_bfe_u32 v229, v175, 4, 2
	v_lshl_add_u32 v228, v229, 3, v228
	v_cvt_pk_bf16_f32 v158, v158, v159
	v_cvt_pk_bf16_f32 v159, v160, v161
	v_cvt_pk_bf16_f32 v154, v154, v155
	v_cvt_pk_bf16_f32 v155, v156, v157
	v_cvt_pk_bf16_f32 v150, v150, v151
	v_cvt_pk_bf16_f32 v151, v152, v153
	v_cvt_pk_bf16_f32 v146, v146, v147
	v_cvt_pk_bf16_f32 v147, v148, v149
	ds_write_b64 v228, v[158:159]
	ds_write_b64 v228, v[154:155] offset:32
	ds_write_b64 v228, v[150:151] offset:64
	ds_write_b64 v228, v[146:147] offset:96
	v_cvt_pk_bf16_f32 v142, v142, v143
	v_cvt_pk_bf16_f32 v143, v144, v145
	v_cvt_pk_bf16_f32 v138, v138, v139
	v_cvt_pk_bf16_f32 v139, v140, v141
	v_cvt_pk_bf16_f32 v134, v134, v135
	v_cvt_pk_bf16_f32 v135, v136, v137
	v_cvt_pk_bf16_f32 v130, v130, v131
	v_cvt_pk_bf16_f32 v131, v132, v133
	ds_write_b64 v228, v[142:143] offset:8448
	ds_write_b64 v228, v[138:139] offset:8480
	ds_write_b64 v228, v[134:135] offset:8512
	ds_write_b64 v228, v[130:131] offset:8544
	v_cvt_pk_bf16_f32 v126, v126, v127
	v_cvt_pk_bf16_f32 v127, v128, v129
	v_cvt_pk_bf16_f32 v122, v122, v123
	v_cvt_pk_bf16_f32 v123, v124, v125
	v_cvt_pk_bf16_f32 v118, v118, v119
	v_cvt_pk_bf16_f32 v119, v120, v121
	v_cvt_pk_bf16_f32 v114, v114, v115
	v_cvt_pk_bf16_f32 v115, v116, v117
	ds_write_b64 v228, v[126:127] offset:16896
	ds_write_b64 v228, v[122:123] offset:16928
	ds_write_b64 v228, v[118:119] offset:16960
	ds_write_b64 v228, v[114:115] offset:16992
	v_cvt_pk_bf16_f32 v110, v110, v111
	v_cvt_pk_bf16_f32 v111, v112, v113
	v_cvt_pk_bf16_f32 v106, v106, v107
	v_cvt_pk_bf16_f32 v107, v108, v109
	v_cvt_pk_bf16_f32 v102, v102, v103
	v_cvt_pk_bf16_f32 v103, v104, v105
	v_cvt_pk_bf16_f32 v98, v98, v99
	v_cvt_pk_bf16_f32 v99, v100, v101
	ds_write_b64 v228, v[110:111] offset:25344
	ds_write_b64 v228, v[106:107] offset:25376
	ds_write_b64 v228, v[102:103] offset:25408
	ds_write_b64 v228, v[98:99] offset:25440
	v_cvt_pk_bf16_f32 v94, v94, v95
	v_cvt_pk_bf16_f32 v95, v96, v97
	v_cvt_pk_bf16_f32 v90, v90, v91
	v_cvt_pk_bf16_f32 v91, v92, v93
	v_cvt_pk_bf16_f32 v86, v86, v87
	v_cvt_pk_bf16_f32 v87, v88, v89
	v_cvt_pk_bf16_f32 v82, v82, v83
	v_cvt_pk_bf16_f32 v83, v84, v85
	ds_write_b64 v228, v[94:95] offset:33792
	ds_write_b64 v228, v[90:91] offset:33824
	ds_write_b64 v228, v[86:87] offset:33856
	ds_write_b64 v228, v[82:83] offset:33888
	v_cvt_pk_bf16_f32 v78, v78, v79
	v_cvt_pk_bf16_f32 v79, v80, v81
	v_cvt_pk_bf16_f32 v74, v74, v75
	v_cvt_pk_bf16_f32 v75, v76, v77
	v_cvt_pk_bf16_f32 v70, v70, v71
	v_cvt_pk_bf16_f32 v71, v72, v73
	v_cvt_pk_bf16_f32 v66, v66, v67
	v_cvt_pk_bf16_f32 v67, v68, v69
	ds_write_b64 v228, v[78:79] offset:42240
	ds_write_b64 v228, v[74:75] offset:42272
	ds_write_b64 v228, v[70:71] offset:42304
	ds_write_b64 v228, v[66:67] offset:42336
	v_cvt_pk_bf16_f32 v62, v62, v63
	v_cvt_pk_bf16_f32 v63, v64, v65
	v_cvt_pk_bf16_f32 v58, v58, v59
	v_cvt_pk_bf16_f32 v59, v60, v61
	v_cvt_pk_bf16_f32 v54, v54, v55
	v_cvt_pk_bf16_f32 v55, v56, v57
	v_cvt_pk_bf16_f32 v50, v50, v51
	v_cvt_pk_bf16_f32 v51, v52, v53
	ds_write_b64 v228, v[62:63] offset:50688
	ds_write_b64 v228, v[58:59] offset:50720
	ds_write_b64 v228, v[54:55] offset:50752
	ds_write_b64 v228, v[50:51] offset:50784
	v_cvt_pk_bf16_f32 v46, v46, v47
	v_cvt_pk_bf16_f32 v47, v48, v49
	v_cvt_pk_bf16_f32 v42, v42, v43
	v_cvt_pk_bf16_f32 v43, v44, v45
	v_cvt_pk_bf16_f32 v38, v38, v39
	v_cvt_pk_bf16_f32 v39, v40, v41
	v_cvt_pk_bf16_f32 v34, v34, v35
	v_cvt_pk_bf16_f32 v35, v36, v37
	ds_write_b64 v228, v[46:47] offset:59136
	ds_write_b64 v228, v[42:43] offset:59168
	ds_write_b64 v228, v[38:39] offset:59200
	ds_write_b64 v228, v[34:35] offset:59232
	v_mov_b32_e32 v43, v175
	s_waitcnt lgkmcnt(0)
	s_barrier
; #define RTID opaque_tid()
; __device__ __forceinline__ void phase_gemm_f32(const u16* A, const u16* Bt, int K, u16* out, u16* smem,
;                                                volatile LAS unsigned* vb_) {
;     ...
;     const int tid2 = RTID;
; #pragma unroll
;     for (int k = 0; k < 16; ++k) {
;       const int c = tid2 + 512 * k;
;       const int row = c >> 5, ch = c & 31;
;       const uint4 v = *(const uint4*)(smem + row * 264 + ch * 8);
;       *(uint4*)(out + (size_t)(mt * 256 + row) * 1024 + nt * 256 + ch * 8) = v;
;     }
;     __syncthreads();
	s_mov_b32 s38, s36
	v_and_b32_e32 v0, 31, v43
	v_lshlrev_b32_e32 v40, 4, v0
	v_mov_b32_e32 v41, 0
	v_ashrrev_i32_e32 v0, 5, v43
	v_mad_u32_u24 v34, v0, s2, v40
	v_add_u32_e32 v35, 0x10800, v34
	ds_read_b128 v[48:51], v34
	ds_read_b128 v[52:55], v34 offset:8448
	ds_read_b128 v[56:59], v34 offset:16896
	ds_read_b128 v[60:63], v34 offset:25344
	ds_read_b128 v[64:67], v34 offset:33792
	ds_read_b128 v[68:71], v34 offset:42240
	ds_read_b128 v[72:75], v34 offset:50688
	ds_read_b128 v[76:79], v34 offset:59136
	v_add_u32_e32 v0, s10, v0
	v_mad_u64_u32 v[38:39], s[12:13], v0, s0, 0
	v_lshl_add_u64 v[38:39], v[38:39], 1, v[40:41]
	v_lshl_add_u64 v[46:47], s[44:45], 0, v[38:39]
	s_lshl_b32 s48, s0, 5
	s_mov_b32 s49, 0
	s_and_b64 vcc, exec, s[42:43]
	s_waitcnt lgkmcnt(7)
	global_store_dwordx4 v[46:47], v[48:51], off
	s_nop 0
	ds_read_b128 v[48:51], v35
	v_lshl_add_u64 v[46:47], v[46:47], 0, s[48:49]
	s_waitcnt lgkmcnt(7)
	global_store_dwordx4 v[46:47], v[52:55], off
	s_nop 0
	ds_read_b128 v[52:55], v35 offset:8448
	v_lshl_add_u64 v[46:47], v[46:47], 0, s[48:49]
	s_waitcnt lgkmcnt(7)
	global_store_dwordx4 v[46:47], v[56:59], off
	s_nop 0
	ds_read_b128 v[56:59], v35 offset:16896
	v_lshl_add_u64 v[46:47], v[46:47], 0, s[48:49]
	s_waitcnt lgkmcnt(7)
	global_store_dwordx4 v[46:47], v[60:63], off
	s_nop 0
	ds_read_b128 v[60:63], v35 offset:25344
	v_lshl_add_u64 v[46:47], v[46:47], 0, s[48:49]
	s_waitcnt lgkmcnt(7)
	global_store_dwordx4 v[46:47], v[64:67], off
	s_nop 0
	ds_read_b128 v[64:67], v35 offset:33792
	v_lshl_add_u64 v[46:47], v[46:47], 0, s[48:49]
	s_waitcnt lgkmcnt(7)
	global_store_dwordx4 v[46:47], v[68:71], off
	s_nop 0
	ds_read_b128 v[68:71], v35 offset:42240
	v_lshl_add_u64 v[46:47], v[46:47], 0, s[48:49]
	s_waitcnt lgkmcnt(7)
	global_store_dwordx4 v[46:47], v[72:75], off
	s_nop 0
	ds_read_b128 v[72:75], v35 offset:50688
	v_lshl_add_u64 v[46:47], v[46:47], 0, s[48:49]
	s_waitcnt lgkmcnt(7)
	global_store_dwordx4 v[46:47], v[76:79], off
	s_nop 0
	ds_read_b128 v[76:79], v35 offset:59136
	v_lshl_add_u64 v[46:47], v[46:47], 0, s[48:49]
	s_waitcnt lgkmcnt(7)
	global_store_dwordx4 v[46:47], v[48:51], off
	v_lshl_add_u64 v[46:47], v[46:47], 0, s[48:49]
	s_waitcnt lgkmcnt(6)
	global_store_dwordx4 v[46:47], v[52:55], off
	v_lshl_add_u64 v[46:47], v[46:47], 0, s[48:49]
	s_waitcnt lgkmcnt(5)
	global_store_dwordx4 v[46:47], v[56:59], off
	v_lshl_add_u64 v[46:47], v[46:47], 0, s[48:49]
	s_waitcnt lgkmcnt(4)
	global_store_dwordx4 v[46:47], v[60:63], off
	v_lshl_add_u64 v[46:47], v[46:47], 0, s[48:49]
	s_waitcnt lgkmcnt(3)
	global_store_dwordx4 v[46:47], v[64:67], off
	v_lshl_add_u64 v[46:47], v[46:47], 0, s[48:49]
	s_waitcnt lgkmcnt(2)
	global_store_dwordx4 v[46:47], v[68:71], off
	v_lshl_add_u64 v[46:47], v[46:47], 0, s[48:49]
	s_waitcnt lgkmcnt(1)
	global_store_dwordx4 v[46:47], v[72:75], off
	v_lshl_add_u64 v[46:47], v[46:47], 0, s[48:49]
	s_waitcnt lgkmcnt(0)
	global_store_dwordx4 v[46:47], v[76:79], off
	s_mov_b64 s[12:13], -1
	s_barrier
	s_cbranch_vccz .LBB0_441

; template <int MI, int NJ> ...
;     ...
;   for (int kt = 0; kt < nk; ++kt) {
;     const int buf = kt & 1;
;     {
;       G8STORE(buf ^ 1);
;       const u16* ga_ = (kt + 2 < nk) ? Ag + (kt + 2) * 64 : Ag + nAoff;
;       const u16* gb_ = (kt + 2 < nk) ? Bg + (kt + 2) * 64 : Bg + nBoff;
;       G8LOADP(ga_, gb_);
;     }
;     __builtin_amdgcn_sched_barrier(0);
;     __builtin_amdgcn_s_setprio(1);
;     const u16* a = ra_ + buf * AROWS * 64;
;     const u16* b = rb_ + buf * BROWS * 64;
; #pragma unroll
;     for (int ks = 0; ks < 2; ++ks) {
;       const u16* a_ = ks ? a + dsw : a;
;       const u16* b_ = ks ? b + dsw : b;
;       bf16x8 bfr[NJ];
; #pragma unroll
;       for (int j = 0; j < NJ; ++j) bfr[j] = *(const bf16x8*)(b_ + j * 16 * 64);
; #pragma unroll
;       for (int ih = 0; ih < MI / 4; ++ih) {
;         bf16x8 af[4];
; #pragma unroll
;         for (int i = 0; i < 4; ++i) af[i] = *(const bf16x8*)(a_ + (ih * 4 + i) * 16 * 64);
; #pragma unroll
;         for (int i = 0; i < 4; ++i)
; #pragma unroll
;           for (int j = 0; j < NJ; ++j) acc[ih * 4 + i][j] = mfma16(af[i], bfr[j], acc[ih * 4 + i][j]);
;       }
;     }
;     __builtin_amdgcn_s_setprio(0);
;     __builtin_amdgcn_sched_barrier(0);
;     __syncthreads();
;   }
.LBB0_601:
	s_waitcnt lgkmcnt(6)
	v_mfma_f32_16x16x32_bf16 v[158:161], v[212:215], v[208:211], v[158:161]
	s_waitcnt lgkmcnt(5)
	v_mfma_f32_16x16x32_bf16 v[154:157], v[216:219], v[208:211], v[154:157]
	s_waitcnt lgkmcnt(4)
	v_mfma_f32_16x16x32_bf16 v[150:153], v[220:223], v[208:211], v[150:153]
	s_waitcnt lgkmcnt(3)
	v_mfma_f32_16x16x32_bf16 v[146:149], v[224:227], v[208:211], v[146:149]
	ds_read_b128 v[208:211], v228 offset:8192
	s_waitcnt lgkmcnt(3)
	v_mfma_f32_16x16x32_bf16 v[142:145], v[212:215], v[234:237], v[142:145]
	v_mfma_f32_16x16x32_bf16 v[138:141], v[216:219], v[234:237], v[138:141]
	v_mfma_f32_16x16x32_bf16 v[134:137], v[220:223], v[234:237], v[134:137]
	v_mfma_f32_16x16x32_bf16 v[130:133], v[224:227], v[234:237], v[130:133]
	ds_read_b128 v[234:237], v228 offset:10240
	s_waitcnt lgkmcnt(3)
	v_mfma_f32_16x16x32_bf16 v[126:129], v[212:215], v[238:241], v[126:129]
	v_mfma_f32_16x16x32_bf16 v[122:125], v[216:219], v[238:241], v[122:125]
	v_mfma_f32_16x16x32_bf16 v[118:121], v[220:223], v[238:241], v[118:121]
	v_mfma_f32_16x16x32_bf16 v[114:117], v[224:227], v[238:241], v[114:117]
	ds_read_b128 v[238:241], v228 offset:12288
	ds_read_b128 v[242:245], v229
	ds_read_b128 v[246:249], v229 offset:2048
	s_waitcnt lgkmcnt(5)
	v_mfma_f32_16x16x32_bf16 v[110:113], v[212:215], v[204:207], v[110:113]
	v_mfma_f32_16x16x32_bf16 v[106:109], v[216:219], v[204:207], v[106:109]
	v_mfma_f32_16x16x32_bf16 v[102:105], v[220:223], v[204:207], v[102:105]
	v_mfma_f32_16x16x32_bf16 v[98:101], v[224:227], v[204:207], v[98:101]
	ds_read_b128 v[204:207], v228 offset:14336
	ds_read_b128 v[190:193], v229 offset:4096
	ds_read_b128 v[170:173], v229 offset:6144
	s_waitcnt lgkmcnt(7)
	v_mfma_f32_16x16x32_bf16 v[94:97], v[212:215], v[208:211], v[94:97]
	v_mfma_f32_16x16x32_bf16 v[90:93], v[216:219], v[208:211], v[90:93]
	v_mfma_f32_16x16x32_bf16 v[86:89], v[220:223], v[208:211], v[86:89]
	v_mfma_f32_16x16x32_bf16 v[82:85], v[224:227], v[208:211], v[82:85]
	v_add_u32_e32 v228, v228, v196
	ds_read_b128 v[208:211], v228
	s_waitcnt vmcnt(7)
	ds_write_b128 v199, v[2:5]
	global_load_dwordx4 v[2:5], v169, s[50:51]
	s_waitcnt lgkmcnt(8)
	v_mfma_f32_16x16x32_bf16 v[78:81], v[212:215], v[234:237], v[78:81]
	v_mfma_f32_16x16x32_bf16 v[74:77], v[216:219], v[234:237], v[74:77]
	v_mfma_f32_16x16x32_bf16 v[70:73], v[220:223], v[234:237], v[70:73]
	v_mfma_f32_16x16x32_bf16 v[66:69], v[224:227], v[234:237], v[66:69]
	ds_read_b128 v[234:237], v228 offset:2048
	s_waitcnt vmcnt(7)
	ds_write_b128 v199, v[6:9] offset:8192
	global_load_dwordx4 v[6:9], v194, s[50:51]
	s_waitcnt lgkmcnt(9)
	v_mfma_f32_16x16x32_bf16 v[62:65], v[212:215], v[238:241], v[62:65]
	v_mfma_f32_16x16x32_bf16 v[58:61], v[216:219], v[238:241], v[58:61]
	v_mfma_f32_16x16x32_bf16 v[54:57], v[220:223], v[238:241], v[54:57]
	v_mfma_f32_16x16x32_bf16 v[50:53], v[224:227], v[238:241], v[50:53]
	ds_read_b128 v[238:241], v228 offset:4096
	s_waitcnt vmcnt(7)
	ds_write_b128 v199, v[10:13] offset:16384
	global_load_dwordx4 v[10:13], v195, s[50:51]
	s_waitcnt lgkmcnt(8)
	v_mfma_f32_16x16x32_bf16 v[46:49], v[212:215], v[204:207], v[46:49]
	v_mfma_f32_16x16x32_bf16 v[42:45], v[216:219], v[204:207], v[42:45]
	v_mfma_f32_16x16x32_bf16 v[38:41], v[220:223], v[204:207], v[38:41]
	v_mfma_f32_16x16x32_bf16 v[34:37], v[224:227], v[204:207], v[34:37]
	ds_read_b128 v[204:207], v228 offset:6144
	s_waitcnt vmcnt(7)
	ds_write_b128 v199, v[18:21] offset:24576
	global_load_dwordx4 v[18:21], v198, s[50:51]
	s_waitcnt lgkmcnt(7)
	v_mfma_f32_16x16x32_bf16 v[158:161], v[242:245], v[208:211], v[158:161]
	v_mfma_f32_16x16x32_bf16 v[154:157], v[246:249], v[208:211], v[154:157]
	v_mfma_f32_16x16x32_bf16 v[150:153], v[190:193], v[208:211], v[150:153]
	v_mfma_f32_16x16x32_bf16 v[146:149], v[170:173], v[208:211], v[146:149]
	ds_read_b128 v[208:211], v228 offset:8192
	s_waitcnt vmcnt(7)
	ds_write_b128 v200, v[14:17]
	global_load_dwordx4 v[14:17], v169, s[52:53]
	s_waitcnt lgkmcnt(7)
	v_mfma_f32_16x16x32_bf16 v[142:145], v[242:245], v[234:237], v[142:145]
	v_mfma_f32_16x16x32_bf16 v[138:141], v[246:249], v[234:237], v[138:141]
	v_mfma_f32_16x16x32_bf16 v[134:137], v[190:193], v[234:237], v[134:137]
	v_mfma_f32_16x16x32_bf16 v[130:133], v[170:173], v[234:237], v[130:133]
	ds_read_b128 v[234:237], v228 offset:10240
	s_waitcnt vmcnt(7)
	ds_write_b128 v200, v[22:25] offset:8192
	global_load_dwordx4 v[22:25], v194, s[52:53]
	s_waitcnt lgkmcnt(7)
	v_mfma_f32_16x16x32_bf16 v[126:129], v[242:245], v[238:241], v[126:129]
	v_mfma_f32_16x16x32_bf16 v[122:125], v[246:249], v[238:241], v[122:125]
	v_mfma_f32_16x16x32_bf16 v[118:121], v[190:193], v[238:241], v[118:121]
	v_mfma_f32_16x16x32_bf16 v[114:117], v[170:173], v[238:241], v[114:117]
	ds_read_b128 v[238:241], v228 offset:12288
	s_waitcnt vmcnt(7)
	ds_write_b128 v200, v[26:29] offset:16384
	global_load_dwordx4 v[26:29], v195, s[52:53]
	s_waitcnt lgkmcnt(7)
	v_mfma_f32_16x16x32_bf16 v[110:113], v[242:245], v[204:207], v[110:113]
	v_mfma_f32_16x16x32_bf16 v[106:109], v[246:249], v[204:207], v[106:109]
	v_mfma_f32_16x16x32_bf16 v[102:105], v[190:193], v[204:207], v[102:105]
	v_mfma_f32_16x16x32_bf16 v[98:101], v[170:173], v[204:207], v[98:101]
	ds_read_b128 v[204:207], v228 offset:14336
	s_waitcnt vmcnt(7)
	ds_write_b128 v200, v[30:33] offset:24576
	global_load_dwordx4 v[30:33], v198, s[52:53]
	s_waitcnt lgkmcnt(7)
	v_mfma_f32_16x16x32_bf16 v[94:97], v[242:245], v[208:211], v[94:97]
	v_mfma_f32_16x16x32_bf16 v[90:93], v[246:249], v[208:211], v[90:93]
	v_mfma_f32_16x16x32_bf16 v[86:89], v[190:193], v[208:211], v[86:89]
	v_mfma_f32_16x16x32_bf16 v[82:85], v[170:173], v[208:211], v[82:85]
	s_waitcnt lgkmcnt(0)
	s_barrier
; __device__ __forceinline__ float siluf_(float x) { return x / (1.0f + __expf(-x)); }
; template <int MI, int NJ> ...
;     ...
;   for (int kt = 0; kt < nk; ++kt) {
;     const int buf = kt & 1;
;     {
;       G8STORE(buf ^ 1);
;       const u16* ga_ = (kt + 2 < nk) ? Ag + (kt + 2) * 64 : Ag + nAoff;
;       const u16* gb_ = (kt + 2 < nk) ? Bg + (kt + 2) * 64 : Bg + nBoff;
;       G8LOADP(ga_, gb_);
;     }
;     __builtin_amdgcn_sched_barrier(0);
;     __builtin_amdgcn_s_setprio(1);
;     const u16* a = ra_ + buf * AROWS * 64;
;     const u16* b = rb_ + buf * BROWS * 64;
; #pragma unroll
;     for (int ks = 0; ks < 2; ++ks) {
;       const u16* a_ = ks ? a + dsw : a;
;       const u16* b_ = ks ? b + dsw : b;
;       bf16x8 bfr[NJ];
; #pragma unroll
;       for (int j = 0; j < NJ; ++j) bfr[j] = *(const bf16x8*)(b_ + j * 16 * 64);
; #pragma unroll
;       for (int ih = 0; ih < MI / 4; ++ih) {
;         bf16x8 af[4];
; #pragma unroll
;         for (int i = 0; i < 4; ++i) af[i] = *(const bf16x8*)(a_ + (ih * 4 + i) * 16 * 64);
; #pragma unroll
;         for (int i = 0; i < 4; ++i)
; #pragma unroll
;           for (int j = 0; j < NJ; ++j) acc[ih * 4 + i][j] = mfma16(af[i], bfr[j], acc[ih * 4 + i][j]);
;       }
;     }
;     __builtin_amdgcn_s_setprio(0);
;     __builtin_amdgcn_sched_barrier(0);
;     __syncthreads();
;   }
; __device__ __forceinline__ void phase_ffn_up(const Params& p, const u16* Wgu, u16* smem, volatile LAS unsigned* vb_) {
;     ...
; #pragma unroll
;     for (int i = 0; i < 8; ++i)
; #pragma unroll
;       for (int jp = 0; jp < 2; ++jp) {
; #pragma unroll
;         for (int r = 0; r < 4; ++r) {
;           const float g = acc[i][2 * jp][r], u = acc[i][2 * jp + 1][r];
;           smem[(wm * 128 + i * 16 + (lane >> 4) * 4 + r) * 136 + (wn * 2 + jp) * 16 + (lane & 15)] = f2bf(siluf_(g) * u);
;         }
;         __builtin_amdgcn_sched_barrier(0);
;       }
	s_add_i32 s43, s43, 1
	s_add_u32 s22, s22, 64
	s_addc_u32 s23, s23, 0
	s_addk_i32 s42, 0x4000
	s_and_b32 s48, s42, 0x4000
	s_xor_b32 s44, s48, 0x4000
	s_lshl_b32 s44, s44, 1
	v_add_u32_e32 v199, s44, v185
	v_add_u32_e32 v200, s44, v186
	s_cmp_lt_u32 s43, 14
	s_cselect_b32 s45, s23, s13
	s_cselect_b32 s44, s22, s12
	s_cselect_b32 s47, s23, s21
	s_cselect_b32 s46, s22, s20
	s_lshl_b64 s[44:45], s[44:45], 1
	s_lshl_b64 s[46:47], s[46:47], 1
	s_add_u32 s50, s62, s44
	s_addc_u32 s51, s63, s45
	s_add_u32 s52, s64, s46
	s_addc_u32 s53, s65, s47
	s_lshl_b32 s44, s48, 1
	v_add_u32_e32 v228, s44, v187
	v_add_u32_e32 v229, s44, v188
	ds_read_b128 v[212:215], v229
	ds_read_b128 v[208:211], v228
	ds_read_b128 v[216:219], v229 offset:2048
	ds_read_b128 v[220:223], v229 offset:4096
	ds_read_b128 v[224:227], v229 offset:6144
	v_mfma_f32_16x16x32_bf16 v[78:81], v[242:245], v[234:237], v[78:81]
	v_mfma_f32_16x16x32_bf16 v[74:77], v[246:249], v[234:237], v[74:77]
	v_mfma_f32_16x16x32_bf16 v[70:73], v[190:193], v[234:237], v[70:73]
	v_mfma_f32_16x16x32_bf16 v[66:69], v[170:173], v[234:237], v[66:69]
	ds_read_b128 v[234:237], v228 offset:2048
	v_mfma_f32_16x16x32_bf16 v[62:65], v[242:245], v[238:241], v[62:65]
	v_mfma_f32_16x16x32_bf16 v[58:61], v[246:249], v[238:241], v[58:61]
	v_mfma_f32_16x16x32_bf16 v[54:57], v[190:193], v[238:241], v[54:57]
	v_mfma_f32_16x16x32_bf16 v[50:53], v[170:173], v[238:241], v[50:53]
	ds_read_b128 v[238:241], v228 offset:4096
	v_mfma_f32_16x16x32_bf16 v[46:49], v[242:245], v[204:207], v[46:49]
	v_mfma_f32_16x16x32_bf16 v[42:45], v[246:249], v[204:207], v[42:45]
	v_mfma_f32_16x16x32_bf16 v[38:41], v[190:193], v[204:207], v[38:41]
	v_mfma_f32_16x16x32_bf16 v[34:37], v[170:173], v[204:207], v[34:37]
	ds_read_b128 v[204:207], v228 offset:6144
	v_add_u32_e32 v229, v229, v196
	s_cmpk_lg_i32 s22, 0x480
	s_cbranch_scc1 .LBB0_601
	v_and_b32_e32 v228, 15, v175
	v_bfe_u32 v229, v175, 8, 1
	v_lshl_or_b32 v228, v229, 7, v228
	v_mul_u32_u24_e32 v228, 0x110, v228
	v_bfe_u32 v229, v175, 6, 2
	v_lshl_add_u32 v228, v229, 6, v228
	v_bfe_u32 v229, v175, 4, 2
	v_lshl_add_u32 v228, v229, 3, v228
	v_mov_b32_e32 v224, 0xbfb8aa3b
	v_mov_b32_e32 v226, 1.0
	v_pk_mul_f32 v[208:209], v[158:159], v[224:225] op_sel_hi:[1,0]
	v_pk_mul_f32 v[210:211], v[160:161], v[224:225] op_sel_hi:[1,0]
	v_pk_mul_f32 v[212:213], v[150:151], v[224:225] op_sel_hi:[1,0]
	v_pk_mul_f32 v[214:215], v[152:153], v[224:225] op_sel_hi:[1,0]
	v_min_f32_e32 v208, 0x42fc0000, v208
	v_min_f32_e32 v209, 0x42fc0000, v209
	v_min_f32_e32 v210, 0x42fc0000, v210
	v_min_f32_e32 v211, 0x42fc0000, v211
	v_min_f32_e32 v212, 0x42fc0000, v212
	v_min_f32_e32 v213, 0x42fc0000, v213
	v_min_f32_e32 v214, 0x42fc0000, v214
	v_min_f32_e32 v215, 0x42fc0000, v215
	v_exp_f32_e32 v208, v208
	v_exp_f32_e32 v209, v209
	v_exp_f32_e32 v210, v210
	v_exp_f32_e32 v211, v211
	v_exp_f32_e32 v212, v212
	v_exp_f32_e32 v213, v213
	v_exp_f32_e32 v214, v214
	v_exp_f32_e32 v215, v215
	v_pk_add_f32 v[208:209], v[208:209], v[226:227] op_sel_hi:[1,0]
	v_pk_add_f32 v[210:211], v[210:211], v[226:227] op_sel_hi:[1,0]
	v_pk_add_f32 v[212:213], v[212:213], v[226:227] op_sel_hi:[1,0]
	v_pk_add_f32 v[214:215], v[214:215], v[226:227] op_sel_hi:[1,0]
	v_rcp_f32_e32 v216, v208
	v_rcp_f32_e32 v217, v209
	v_rcp_f32_e32 v218, v210
	v_rcp_f32_e32 v219, v211
	v_rcp_f32_e32 v220, v212
	v_rcp_f32_e32 v221, v213
	v_rcp_f32_e32 v222, v214
	v_rcp_f32_e32 v223, v215
	v_pk_fma_f32 v[208:209], v[208:209], v[216:217], v[226:227] op_sel_hi:[1,1,0] neg_lo:[1,0,0] neg_hi:[1,0,0]
	v_pk_fma_f32 v[210:211], v[210:211], v[218:219], v[226:227] op_sel_hi:[1,1,0] neg_lo:[1,0,0] neg_hi:[1,0,0]
	v_pk_fma_f32 v[212:213], v[212:213], v[220:221], v[226:227] op_sel_hi:[1,1,0] neg_lo:[1,0,0] neg_hi:[1,0,0]
	v_pk_fma_f32 v[214:215], v[214:215], v[222:223], v[226:227] op_sel_hi:[1,1,0] neg_lo:[1,0,0] neg_hi:[1,0,0]
	v_pk_fma_f32 v[216:217], v[208:209], v[216:217], v[216:217]
	v_pk_fma_f32 v[218:219], v[210:211], v[218:219], v[218:219]
	v_pk_fma_f32 v[220:221], v[212:213], v[220:221], v[220:221]
	v_pk_fma_f32 v[222:223], v[214:215], v[222:223], v[222:223]
	v_pk_mul_f32 v[158:159], v[158:159], v[216:217]
	v_pk_mul_f32 v[160:161], v[160:161], v[218:219]
	v_pk_mul_f32 v[150:151], v[150:151], v[220:221]
	v_pk_mul_f32 v[152:153], v[152:153], v[222:223]
	v_pk_mul_f32 v[158:159], v[158:159], v[154:155]
	v_pk_mul_f32 v[160:161], v[160:161], v[156:157]
	v_pk_mul_f32 v[150:151], v[150:151], v[146:147]
	v_pk_mul_f32 v[152:153], v[152:153], v[148:149]
	v_cvt_pk_bf16_f32 v158, v158, v159
	v_cvt_pk_bf16_f32 v159, v160, v161
	v_cvt_pk_bf16_f32 v150, v150, v151
	v_cvt_pk_bf16_f32 v151, v152, v153
	ds_write_b64 v228, v[158:159]
	ds_write_b64 v228, v[150:151] offset:32
	v_pk_mul_f32 v[208:209], v[142:143], v[224:225] op_sel_hi:[1,0]
	v_pk_mul_f32 v[210:211], v[144:145], v[224:225] op_sel_hi:[1,0]
	v_pk_mul_f32 v[212:213], v[134:135], v[224:225] op_sel_hi:[1,0]
	v_pk_mul_f32 v[214:215], v[136:137], v[224:225] op_sel_hi:[1,0]
	v_min_f32_e32 v208, 0x42fc0000, v208
	v_min_f32_e32 v209, 0x42fc0000, v209
	v_min_f32_e32 v210, 0x42fc0000, v210
	v_min_f32_e32 v211, 0x42fc0000, v211
	v_min_f32_e32 v212, 0x42fc0000, v212
	v_min_f32_e32 v213, 0x42fc0000, v213
	v_min_f32_e32 v214, 0x42fc0000, v214
	v_min_f32_e32 v215, 0x42fc0000, v215
	v_exp_f32_e32 v208, v208
	v_exp_f32_e32 v209, v209
	v_exp_f32_e32 v210, v210
	v_exp_f32_e32 v211, v211
	v_exp_f32_e32 v212, v212
	v_exp_f32_e32 v213, v213
	v_exp_f32_e32 v214, v214
	v_exp_f32_e32 v215, v215
	v_pk_add_f32 v[208:209], v[208:209], v[226:227] op_sel_hi:[1,0]
	v_pk_add_f32 v[210:211], v[210:211], v[226:227] op_sel_hi:[1,0]
; __device__ __forceinline__ float siluf_(float x) { return x / (1.0f + __expf(-x)); }
; __device__ __forceinline__ void phase_ffn_up(const Params& p, const u16* Wgu, u16* smem, volatile LAS unsigned* vb_) {
;     ...
; #pragma unroll
;     for (int i = 0; i < 8; ++i)
; #pragma unroll
;       for (int jp = 0; jp < 2; ++jp) {
; #pragma unroll
;         for (int r = 0; r < 4; ++r) {
;           const float g = acc[i][2 * jp][r], u = acc[i][2 * jp + 1][r];
;           smem[(wm * 128 + i * 16 + (lane >> 4) * 4 + r) * 136 + (wn * 2 + jp) * 16 + (lane & 15)] = f2bf(siluf_(g) * u);
;         }
;         __builtin_amdgcn_sched_barrier(0);
;       }
	v_pk_add_f32 v[212:213], v[212:213], v[226:227] op_sel_hi:[1,0]
	v_pk_add_f32 v[214:215], v[214:215], v[226:227] op_sel_hi:[1,0]
	v_rcp_f32_e32 v216, v208
	v_rcp_f32_e32 v217, v209
	v_rcp_f32_e32 v218, v210
	v_rcp_f32_e32 v219, v211
	v_rcp_f32_e32 v220, v212
	v_rcp_f32_e32 v221, v213
	v_rcp_f32_e32 v222, v214
	v_rcp_f32_e32 v223, v215
	v_pk_fma_f32 v[208:209], v[208:209], v[216:217], v[226:227] op_sel_hi:[1,1,0] neg_lo:[1,0,0] neg_hi:[1,0,0]
	v_pk_fma_f32 v[210:211], v[210:211], v[218:219], v[226:227] op_sel_hi:[1,1,0] neg_lo:[1,0,0] neg_hi:[1,0,0]
	v_pk_fma_f32 v[212:213], v[212:213], v[220:221], v[226:227] op_sel_hi:[1,1,0] neg_lo:[1,0,0] neg_hi:[1,0,0]
	v_pk_fma_f32 v[214:215], v[214:215], v[222:223], v[226:227] op_sel_hi:[1,1,0] neg_lo:[1,0,0] neg_hi:[1,0,0]
	v_pk_fma_f32 v[216:217], v[208:209], v[216:217], v[216:217]
	v_pk_fma_f32 v[218:219], v[210:211], v[218:219], v[218:219]
	v_pk_fma_f32 v[220:221], v[212:213], v[220:221], v[220:221]
	v_pk_fma_f32 v[222:223], v[214:215], v[222:223], v[222:223]
	v_pk_mul_f32 v[142:143], v[142:143], v[216:217]
	v_pk_mul_f32 v[144:145], v[144:145], v[218:219]
	v_pk_mul_f32 v[134:135], v[134:135], v[220:221]
	v_pk_mul_f32 v[136:137], v[136:137], v[222:223]
	v_pk_mul_f32 v[142:143], v[142:143], v[138:139]
	v_pk_mul_f32 v[144:145], v[144:145], v[140:141]
	v_pk_mul_f32 v[134:135], v[134:135], v[130:131]
	v_pk_mul_f32 v[136:137], v[136:137], v[132:133]
	v_cvt_pk_bf16_f32 v142, v142, v143
	v_cvt_pk_bf16_f32 v143, v144, v145
	v_cvt_pk_bf16_f32 v134, v134, v135
	v_cvt_pk_bf16_f32 v135, v136, v137
	ds_write_b64 v228, v[142:143] offset:4352
	ds_write_b64 v228, v[134:135] offset:4384
	v_pk_mul_f32 v[208:209], v[126:127], v[224:225] op_sel_hi:[1,0]
	v_pk_mul_f32 v[210:211], v[128:129], v[224:225] op_sel_hi:[1,0]
	v_pk_mul_f32 v[212:213], v[118:119], v[224:225] op_sel_hi:[1,0]
	v_pk_mul_f32 v[214:215], v[120:121], v[224:225] op_sel_hi:[1,0]
	v_min_f32_e32 v208, 0x42fc0000, v208
	v_min_f32_e32 v209, 0x42fc0000, v209
	v_min_f32_e32 v210, 0x42fc0000, v210
	v_min_f32_e32 v211, 0x42fc0000, v211
	v_min_f32_e32 v212, 0x42fc0000, v212
	v_min_f32_e32 v213, 0x42fc0000, v213
	v_min_f32_e32 v214, 0x42fc0000, v214
	v_min_f32_e32 v215, 0x42fc0000, v215
	v_exp_f32_e32 v208, v208
	v_exp_f32_e32 v209, v209
	v_exp_f32_e32 v210, v210
	v_exp_f32_e32 v211, v211
	v_exp_f32_e32 v212, v212
	v_exp_f32_e32 v213, v213
	v_exp_f32_e32 v214, v214
	v_exp_f32_e32 v215, v215
	v_pk_add_f32 v[208:209], v[208:209], v[226:227] op_sel_hi:[1,0]
	v_pk_add_f32 v[210:211], v[210:211], v[226:227] op_sel_hi:[1,0]
	v_pk_add_f32 v[212:213], v[212:213], v[226:227] op_sel_hi:[1,0]
	v_pk_add_f32 v[214:215], v[214:215], v[226:227] op_sel_hi:[1,0]
	v_rcp_f32_e32 v216, v208
	v_rcp_f32_e32 v217, v209
	v_rcp_f32_e32 v218, v210
	v_rcp_f32_e32 v219, v211
	v_rcp_f32_e32 v220, v212
	v_rcp_f32_e32 v221, v213
	v_rcp_f32_e32 v222, v214
	v_rcp_f32_e32 v223, v215
	v_pk_fma_f32 v[208:209], v[208:209], v[216:217], v[226:227] op_sel_hi:[1,1,0] neg_lo:[1,0,0] neg_hi:[1,0,0]
	v_pk_fma_f32 v[210:211], v[210:211], v[218:219], v[226:227] op_sel_hi:[1,1,0] neg_lo:[1,0,0] neg_hi:[1,0,0]
	v_pk_fma_f32 v[212:213], v[212:213], v[220:221], v[226:227] op_sel_hi:[1,1,0] neg_lo:[1,0,0] neg_hi:[1,0,0]
	v_pk_fma_f32 v[214:215], v[214:215], v[222:223], v[226:227] op_sel_hi:[1,1,0] neg_lo:[1,0,0] neg_hi:[1,0,0]
	v_pk_fma_f32 v[216:217], v[208:209], v[216:217], v[216:217]
	v_pk_fma_f32 v[218:219], v[210:211], v[218:219], v[218:219]
	v_pk_fma_f32 v[220:221], v[212:213], v[220:221], v[220:221]
	v_pk_fma_f32 v[222:223], v[214:215], v[222:223], v[222:223]
	v_pk_mul_f32 v[126:127], v[126:127], v[216:217]
	v_pk_mul_f32 v[128:129], v[128:129], v[218:219]
	v_pk_mul_f32 v[118:119], v[118:119], v[220:221]
	v_pk_mul_f32 v[120:121], v[120:121], v[222:223]
	v_pk_mul_f32 v[126:127], v[126:127], v[122:123]
	v_pk_mul_f32 v[128:129], v[128:129], v[124:125]
	v_pk_mul_f32 v[118:119], v[118:119], v[114:115]
	v_pk_mul_f32 v[120:121], v[120:121], v[116:117]
	v_cvt_pk_bf16_f32 v126, v126, v127
	v_cvt_pk_bf16_f32 v127, v128, v129
	v_cvt_pk_bf16_f32 v118, v118, v119
	v_cvt_pk_bf16_f32 v119, v120, v121
	ds_write_b64 v228, v[126:127] offset:8704
	ds_write_b64 v228, v[118:119] offset:8736
	v_pk_mul_f32 v[208:209], v[110:111], v[224:225] op_sel_hi:[1,0]
	v_pk_mul_f32 v[210:211], v[112:113], v[224:225] op_sel_hi:[1,0]
	v_pk_mul_f32 v[212:213], v[102:103], v[224:225] op_sel_hi:[1,0]
	v_pk_mul_f32 v[214:215], v[104:105], v[224:225] op_sel_hi:[1,0]
	v_min_f32_e32 v208, 0x42fc0000, v208
	v_min_f32_e32 v209, 0x42fc0000, v209
	v_min_f32_e32 v210, 0x42fc0000, v210
	v_min_f32_e32 v211, 0x42fc0000, v211
	v_min_f32_e32 v212, 0x42fc0000, v212
	v_min_f32_e32 v213, 0x42fc0000, v213
	v_min_f32_e32 v214, 0x42fc0000, v214
	v_min_f32_e32 v215, 0x42fc0000, v215
	v_exp_f32_e32 v208, v208
	v_exp_f32_e32 v209, v209
	v_exp_f32_e32 v210, v210
	v_exp_f32_e32 v211, v211
	v_exp_f32_e32 v212, v212
	v_exp_f32_e32 v213, v213
	v_exp_f32_e32 v214, v214
	v_exp_f32_e32 v215, v215
	v_pk_add_f32 v[208:209], v[208:209], v[226:227] op_sel_hi:[1,0]
	v_pk_add_f32 v[210:211], v[210:211], v[226:227] op_sel_hi:[1,0]
	v_pk_add_f32 v[212:213], v[212:213], v[226:227] op_sel_hi:[1,0]
	v_pk_add_f32 v[214:215], v[214:215], v[226:227] op_sel_hi:[1,0]
	v_rcp_f32_e32 v216, v208
	v_rcp_f32_e32 v217, v209
	v_rcp_f32_e32 v218, v210
	v_rcp_f32_e32 v219, v211
	v_rcp_f32_e32 v220, v212
	v_rcp_f32_e32 v221, v213
	v_rcp_f32_e32 v222, v214
	v_rcp_f32_e32 v223, v215
	v_pk_fma_f32 v[208:209], v[208:209], v[216:217], v[226:227] op_sel_hi:[1,1,0] neg_lo:[1,0,0] neg_hi:[1,0,0]
	v_pk_fma_f32 v[210:211], v[210:211], v[218:219], v[226:227] op_sel_hi:[1,1,0] neg_lo:[1,0,0] neg_hi:[1,0,0]
; __device__ __forceinline__ float siluf_(float x) { return x / (1.0f + __expf(-x)); }
; __device__ __forceinline__ void phase_ffn_up(const Params& p, const u16* Wgu, u16* smem, volatile LAS unsigned* vb_) {
;     ...
; #pragma unroll
;     for (int i = 0; i < 8; ++i)
; #pragma unroll
;       for (int jp = 0; jp < 2; ++jp) {
; #pragma unroll
;         for (int r = 0; r < 4; ++r) {
;           const float g = acc[i][2 * jp][r], u = acc[i][2 * jp + 1][r];
;           smem[(wm * 128 + i * 16 + (lane >> 4) * 4 + r) * 136 + (wn * 2 + jp) * 16 + (lane & 15)] = f2bf(siluf_(g) * u);
;         }
;         __builtin_amdgcn_sched_barrier(0);
;       }
	v_pk_fma_f32 v[212:213], v[212:213], v[220:221], v[226:227] op_sel_hi:[1,1,0] neg_lo:[1,0,0] neg_hi:[1,0,0]
	v_pk_fma_f32 v[214:215], v[214:215], v[222:223], v[226:227] op_sel_hi:[1,1,0] neg_lo:[1,0,0] neg_hi:[1,0,0]
	v_pk_fma_f32 v[216:217], v[208:209], v[216:217], v[216:217]
	v_pk_fma_f32 v[218:219], v[210:211], v[218:219], v[218:219]
	v_pk_fma_f32 v[220:221], v[212:213], v[220:221], v[220:221]
	v_pk_fma_f32 v[222:223], v[214:215], v[222:223], v[222:223]
	v_pk_mul_f32 v[110:111], v[110:111], v[216:217]
	v_pk_mul_f32 v[112:113], v[112:113], v[218:219]
	v_pk_mul_f32 v[102:103], v[102:103], v[220:221]
	v_pk_mul_f32 v[104:105], v[104:105], v[222:223]
	v_pk_mul_f32 v[110:111], v[110:111], v[106:107]
	v_pk_mul_f32 v[112:113], v[112:113], v[108:109]
	v_pk_mul_f32 v[102:103], v[102:103], v[98:99]
	v_pk_mul_f32 v[104:105], v[104:105], v[100:101]
	v_cvt_pk_bf16_f32 v110, v110, v111
	v_cvt_pk_bf16_f32 v111, v112, v113
	v_cvt_pk_bf16_f32 v102, v102, v103
	v_cvt_pk_bf16_f32 v103, v104, v105
	ds_write_b64 v228, v[110:111] offset:13056
	ds_write_b64 v228, v[102:103] offset:13088
	v_pk_mul_f32 v[208:209], v[94:95], v[224:225] op_sel_hi:[1,0]
	v_pk_mul_f32 v[210:211], v[96:97], v[224:225] op_sel_hi:[1,0]
	v_pk_mul_f32 v[212:213], v[86:87], v[224:225] op_sel_hi:[1,0]
	v_pk_mul_f32 v[214:215], v[88:89], v[224:225] op_sel_hi:[1,0]
	v_min_f32_e32 v208, 0x42fc0000, v208
	v_min_f32_e32 v209, 0x42fc0000, v209
	v_min_f32_e32 v210, 0x42fc0000, v210
	v_min_f32_e32 v211, 0x42fc0000, v211
	v_min_f32_e32 v212, 0x42fc0000, v212
	v_min_f32_e32 v213, 0x42fc0000, v213
	v_min_f32_e32 v214, 0x42fc0000, v214
	v_min_f32_e32 v215, 0x42fc0000, v215
	v_exp_f32_e32 v208, v208
	v_exp_f32_e32 v209, v209
	v_exp_f32_e32 v210, v210
	v_exp_f32_e32 v211, v211
	v_exp_f32_e32 v212, v212
	v_exp_f32_e32 v213, v213
	v_exp_f32_e32 v214, v214
	v_exp_f32_e32 v215, v215
	v_pk_add_f32 v[208:209], v[208:209], v[226:227] op_sel_hi:[1,0]
	v_pk_add_f32 v[210:211], v[210:211], v[226:227] op_sel_hi:[1,0]
	v_pk_add_f32 v[212:213], v[212:213], v[226:227] op_sel_hi:[1,0]
	v_pk_add_f32 v[214:215], v[214:215], v[226:227] op_sel_hi:[1,0]
	v_rcp_f32_e32 v216, v208
	v_rcp_f32_e32 v217, v209
	v_rcp_f32_e32 v218, v210
	v_rcp_f32_e32 v219, v211
	v_rcp_f32_e32 v220, v212
	v_rcp_f32_e32 v221, v213
	v_rcp_f32_e32 v222, v214
	v_rcp_f32_e32 v223, v215
	v_pk_fma_f32 v[208:209], v[208:209], v[216:217], v[226:227] op_sel_hi:[1,1,0] neg_lo:[1,0,0] neg_hi:[1,0,0]
	v_pk_fma_f32 v[210:211], v[210:211], v[218:219], v[226:227] op_sel_hi:[1,1,0] neg_lo:[1,0,0] neg_hi:[1,0,0]
	v_pk_fma_f32 v[212:213], v[212:213], v[220:221], v[226:227] op_sel_hi:[1,1,0] neg_lo:[1,0,0] neg_hi:[1,0,0]
	v_pk_fma_f32 v[214:215], v[214:215], v[222:223], v[226:227] op_sel_hi:[1,1,0] neg_lo:[1,0,0] neg_hi:[1,0,0]
	v_pk_fma_f32 v[216:217], v[208:209], v[216:217], v[216:217]
	v_pk_fma_f32 v[218:219], v[210:211], v[218:219], v[218:219]
	v_pk_fma_f32 v[220:221], v[212:213], v[220:221], v[220:221]
	v_pk_fma_f32 v[222:223], v[214:215], v[222:223], v[222:223]
	v_pk_mul_f32 v[94:95], v[94:95], v[216:217]
	v_pk_mul_f32 v[96:97], v[96:97], v[218:219]
	v_pk_mul_f32 v[86:87], v[86:87], v[220:221]
	v_pk_mul_f32 v[88:89], v[88:89], v[222:223]
	v_pk_mul_f32 v[94:95], v[94:95], v[90:91]
	v_pk_mul_f32 v[96:97], v[96:97], v[92:93]
	v_pk_mul_f32 v[86:87], v[86:87], v[82:83]
	v_pk_mul_f32 v[88:89], v[88:89], v[84:85]
	v_cvt_pk_bf16_f32 v94, v94, v95
	v_cvt_pk_bf16_f32 v95, v96, v97
	v_cvt_pk_bf16_f32 v86, v86, v87
	v_cvt_pk_bf16_f32 v87, v88, v89
	ds_write_b64 v228, v[94:95] offset:17408
	ds_write_b64 v228, v[86:87] offset:17440
	v_pk_mul_f32 v[208:209], v[78:79], v[224:225] op_sel_hi:[1,0]
	v_pk_mul_f32 v[210:211], v[80:81], v[224:225] op_sel_hi:[1,0]
	v_pk_mul_f32 v[212:213], v[70:71], v[224:225] op_sel_hi:[1,0]
	v_pk_mul_f32 v[214:215], v[72:73], v[224:225] op_sel_hi:[1,0]
	v_min_f32_e32 v208, 0x42fc0000, v208
	v_min_f32_e32 v209, 0x42fc0000, v209
	v_min_f32_e32 v210, 0x42fc0000, v210
	v_min_f32_e32 v211, 0x42fc0000, v211
	v_min_f32_e32 v212, 0x42fc0000, v212
	v_min_f32_e32 v213, 0x42fc0000, v213
	v_min_f32_e32 v214, 0x42fc0000, v214
	v_min_f32_e32 v215, 0x42fc0000, v215
	v_exp_f32_e32 v208, v208
	v_exp_f32_e32 v209, v209
	v_exp_f32_e32 v210, v210
	v_exp_f32_e32 v211, v211
	v_exp_f32_e32 v212, v212
	v_exp_f32_e32 v213, v213
	v_exp_f32_e32 v214, v214
	v_exp_f32_e32 v215, v215
	v_pk_add_f32 v[208:209], v[208:209], v[226:227] op_sel_hi:[1,0]
	v_pk_add_f32 v[210:211], v[210:211], v[226:227] op_sel_hi:[1,0]
	v_pk_add_f32 v[212:213], v[212:213], v[226:227] op_sel_hi:[1,0]
	v_pk_add_f32 v[214:215], v[214:215], v[226:227] op_sel_hi:[1,0]
	v_rcp_f32_e32 v216, v208
	v_rcp_f32_e32 v217, v209
	v_rcp_f32_e32 v218, v210
	v_rcp_f32_e32 v219, v211
	v_rcp_f32_e32 v220, v212
	v_rcp_f32_e32 v221, v213
	v_rcp_f32_e32 v222, v214
	v_rcp_f32_e32 v223, v215
	v_pk_fma_f32 v[208:209], v[208:209], v[216:217], v[226:227] op_sel_hi:[1,1,0] neg_lo:[1,0,0] neg_hi:[1,0,0]
	v_pk_fma_f32 v[210:211], v[210:211], v[218:219], v[226:227] op_sel_hi:[1,1,0] neg_lo:[1,0,0] neg_hi:[1,0,0]
	v_pk_fma_f32 v[212:213], v[212:213], v[220:221], v[226:227] op_sel_hi:[1,1,0] neg_lo:[1,0,0] neg_hi:[1,0,0]
	v_pk_fma_f32 v[214:215], v[214:215], v[222:223], v[226:227] op_sel_hi:[1,1,0] neg_lo:[1,0,0] neg_hi:[1,0,0]
	v_pk_fma_f32 v[216:217], v[208:209], v[216:217], v[216:217]
	v_pk_fma_f32 v[218:219], v[210:211], v[218:219], v[218:219]
	v_pk_fma_f32 v[220:221], v[212:213], v[220:221], v[220:221]
	v_pk_fma_f32 v[222:223], v[214:215], v[222:223], v[222:223]
	v_pk_mul_f32 v[78:79], v[78:79], v[216:217]
	v_pk_mul_f32 v[80:81], v[80:81], v[218:219]
	v_pk_mul_f32 v[70:71], v[70:71], v[220:221]
	v_pk_mul_f32 v[72:73], v[72:73], v[222:223]
; __device__ __forceinline__ float siluf_(float x) { return x / (1.0f + __expf(-x)); }
; __device__ __forceinline__ void phase_ffn_up(const Params& p, const u16* Wgu, u16* smem, volatile LAS unsigned* vb_) {
;     ...
; #pragma unroll
;     for (int i = 0; i < 8; ++i)
; #pragma unroll
;       for (int jp = 0; jp < 2; ++jp) {
; #pragma unroll
;         for (int r = 0; r < 4; ++r) {
;           const float g = acc[i][2 * jp][r], u = acc[i][2 * jp + 1][r];
;           smem[(wm * 128 + i * 16 + (lane >> 4) * 4 + r) * 136 + (wn * 2 + jp) * 16 + (lane & 15)] = f2bf(siluf_(g) * u);
;         }
;         __builtin_amdgcn_sched_barrier(0);
;       }
;     __syncthreads();
; #pragma unroll
;     for (int k = 0; k < 8; ++k) {
;       const int c = tid + 512 * k;
;       const int row = c >> 4, ch = c & 15;
;       const uint4 v = *(const uint4*)(smem + row * 136 + ch * 8);
;       *(uint4*)(act + (size_t)(mt * 256 + row) * DFF + nt * 128 + ch * 8) = v;
;     }
;     __syncthreads();
	v_pk_mul_f32 v[78:79], v[78:79], v[74:75]
	v_pk_mul_f32 v[80:81], v[80:81], v[76:77]
	v_pk_mul_f32 v[70:71], v[70:71], v[66:67]
	v_pk_mul_f32 v[72:73], v[72:73], v[68:69]
	v_cvt_pk_bf16_f32 v78, v78, v79
	v_cvt_pk_bf16_f32 v79, v80, v81
	v_cvt_pk_bf16_f32 v70, v70, v71
	v_cvt_pk_bf16_f32 v71, v72, v73
	ds_write_b64 v228, v[78:79] offset:21760
	ds_write_b64 v228, v[70:71] offset:21792
	v_pk_mul_f32 v[208:209], v[62:63], v[224:225] op_sel_hi:[1,0]
	v_pk_mul_f32 v[210:211], v[64:65], v[224:225] op_sel_hi:[1,0]
	v_pk_mul_f32 v[212:213], v[54:55], v[224:225] op_sel_hi:[1,0]
	v_pk_mul_f32 v[214:215], v[56:57], v[224:225] op_sel_hi:[1,0]
	v_min_f32_e32 v208, 0x42fc0000, v208
	v_min_f32_e32 v209, 0x42fc0000, v209
	v_min_f32_e32 v210, 0x42fc0000, v210
	v_min_f32_e32 v211, 0x42fc0000, v211
	v_min_f32_e32 v212, 0x42fc0000, v212
	v_min_f32_e32 v213, 0x42fc0000, v213
	v_min_f32_e32 v214, 0x42fc0000, v214
	v_min_f32_e32 v215, 0x42fc0000, v215
	v_exp_f32_e32 v208, v208
	v_exp_f32_e32 v209, v209
	v_exp_f32_e32 v210, v210
	v_exp_f32_e32 v211, v211
	v_exp_f32_e32 v212, v212
	v_exp_f32_e32 v213, v213
	v_exp_f32_e32 v214, v214
	v_exp_f32_e32 v215, v215
	v_pk_add_f32 v[208:209], v[208:209], v[226:227] op_sel_hi:[1,0]
	v_pk_add_f32 v[210:211], v[210:211], v[226:227] op_sel_hi:[1,0]
	v_pk_add_f32 v[212:213], v[212:213], v[226:227] op_sel_hi:[1,0]
	v_pk_add_f32 v[214:215], v[214:215], v[226:227] op_sel_hi:[1,0]
	v_rcp_f32_e32 v216, v208
	v_rcp_f32_e32 v217, v209
	v_rcp_f32_e32 v218, v210
	v_rcp_f32_e32 v219, v211
	v_rcp_f32_e32 v220, v212
	v_rcp_f32_e32 v221, v213
	v_rcp_f32_e32 v222, v214
	v_rcp_f32_e32 v223, v215
	v_pk_fma_f32 v[208:209], v[208:209], v[216:217], v[226:227] op_sel_hi:[1,1,0] neg_lo:[1,0,0] neg_hi:[1,0,0]
	v_pk_fma_f32 v[210:211], v[210:211], v[218:219], v[226:227] op_sel_hi:[1,1,0] neg_lo:[1,0,0] neg_hi:[1,0,0]
	v_pk_fma_f32 v[212:213], v[212:213], v[220:221], v[226:227] op_sel_hi:[1,1,0] neg_lo:[1,0,0] neg_hi:[1,0,0]
	v_pk_fma_f32 v[214:215], v[214:215], v[222:223], v[226:227] op_sel_hi:[1,1,0] neg_lo:[1,0,0] neg_hi:[1,0,0]
	v_pk_fma_f32 v[216:217], v[208:209], v[216:217], v[216:217]
	v_pk_fma_f32 v[218:219], v[210:211], v[218:219], v[218:219]
	v_pk_fma_f32 v[220:221], v[212:213], v[220:221], v[220:221]
	v_pk_fma_f32 v[222:223], v[214:215], v[222:223], v[222:223]
	v_pk_mul_f32 v[62:63], v[62:63], v[216:217]
	v_pk_mul_f32 v[64:65], v[64:65], v[218:219]
	v_pk_mul_f32 v[54:55], v[54:55], v[220:221]
	v_pk_mul_f32 v[56:57], v[56:57], v[222:223]
	v_pk_mul_f32 v[62:63], v[62:63], v[58:59]
	v_pk_mul_f32 v[64:65], v[64:65], v[60:61]
	v_pk_mul_f32 v[54:55], v[54:55], v[50:51]
	v_pk_mul_f32 v[56:57], v[56:57], v[52:53]
	v_cvt_pk_bf16_f32 v62, v62, v63
	v_cvt_pk_bf16_f32 v63, v64, v65
	v_cvt_pk_bf16_f32 v54, v54, v55
	v_cvt_pk_bf16_f32 v55, v56, v57
	ds_write_b64 v228, v[62:63] offset:26112
	ds_write_b64 v228, v[54:55] offset:26144
	v_pk_mul_f32 v[208:209], v[46:47], v[224:225] op_sel_hi:[1,0]
	v_pk_mul_f32 v[210:211], v[48:49], v[224:225] op_sel_hi:[1,0]
	v_pk_mul_f32 v[212:213], v[38:39], v[224:225] op_sel_hi:[1,0]
	v_pk_mul_f32 v[214:215], v[40:41], v[224:225] op_sel_hi:[1,0]
	v_min_f32_e32 v208, 0x42fc0000, v208
	v_min_f32_e32 v209, 0x42fc0000, v209
	v_min_f32_e32 v210, 0x42fc0000, v210
	v_min_f32_e32 v211, 0x42fc0000, v211
	v_min_f32_e32 v212, 0x42fc0000, v212
	v_min_f32_e32 v213, 0x42fc0000, v213
	v_min_f32_e32 v214, 0x42fc0000, v214
	v_min_f32_e32 v215, 0x42fc0000, v215
	v_exp_f32_e32 v208, v208
	v_exp_f32_e32 v209, v209
	v_exp_f32_e32 v210, v210
	v_exp_f32_e32 v211, v211
	v_exp_f32_e32 v212, v212
	v_exp_f32_e32 v213, v213
	v_exp_f32_e32 v214, v214
	v_exp_f32_e32 v215, v215
	v_pk_add_f32 v[208:209], v[208:209], v[226:227] op_sel_hi:[1,0]
	v_pk_add_f32 v[210:211], v[210:211], v[226:227] op_sel_hi:[1,0]
	v_pk_add_f32 v[212:213], v[212:213], v[226:227] op_sel_hi:[1,0]
	v_pk_add_f32 v[214:215], v[214:215], v[226:227] op_sel_hi:[1,0]
	v_rcp_f32_e32 v216, v208
	v_rcp_f32_e32 v217, v209
	v_rcp_f32_e32 v218, v210
	v_rcp_f32_e32 v219, v211
	v_rcp_f32_e32 v220, v212
	v_rcp_f32_e32 v221, v213
	v_rcp_f32_e32 v222, v214
	v_rcp_f32_e32 v223, v215
	v_pk_fma_f32 v[208:209], v[208:209], v[216:217], v[226:227] op_sel_hi:[1,1,0] neg_lo:[1,0,0] neg_hi:[1,0,0]
	v_pk_fma_f32 v[210:211], v[210:211], v[218:219], v[226:227] op_sel_hi:[1,1,0] neg_lo:[1,0,0] neg_hi:[1,0,0]
	v_pk_fma_f32 v[212:213], v[212:213], v[220:221], v[226:227] op_sel_hi:[1,1,0] neg_lo:[1,0,0] neg_hi:[1,0,0]
	v_pk_fma_f32 v[214:215], v[214:215], v[222:223], v[226:227] op_sel_hi:[1,1,0] neg_lo:[1,0,0] neg_hi:[1,0,0]
	v_pk_fma_f32 v[216:217], v[208:209], v[216:217], v[216:217]
	v_pk_fma_f32 v[218:219], v[210:211], v[218:219], v[218:219]
	v_pk_fma_f32 v[220:221], v[212:213], v[220:221], v[220:221]
	v_pk_fma_f32 v[222:223], v[214:215], v[222:223], v[222:223]
	v_pk_mul_f32 v[46:47], v[46:47], v[216:217]
	v_pk_mul_f32 v[48:49], v[48:49], v[218:219]
	v_pk_mul_f32 v[38:39], v[38:39], v[220:221]
	v_pk_mul_f32 v[40:41], v[40:41], v[222:223]
	v_pk_mul_f32 v[46:47], v[46:47], v[42:43]
	v_pk_mul_f32 v[48:49], v[48:49], v[44:45]
	v_pk_mul_f32 v[38:39], v[38:39], v[34:35]
	v_pk_mul_f32 v[40:41], v[40:41], v[36:37]
	v_cvt_pk_bf16_f32 v46, v46, v47
	v_cvt_pk_bf16_f32 v47, v48, v49
	v_cvt_pk_bf16_f32 v38, v38, v39
	v_cvt_pk_bf16_f32 v39, v40, v41
	ds_write_b64 v228, v[46:47] offset:30464
	ds_write_b64 v228, v[38:39] offset:30496
	s_waitcnt lgkmcnt(0)
	s_barrier
	s_lshl_b32 s12, s40, 7
	s_ashr_i32 s13, s12, 31
	v_lshl_add_u64 v[38:39], s[12:13], 1, v[166:167]
	s_and_b64 vcc, exec, s[10:11]
	s_mov_b32 s20, s41
	ds_read_b128 v[42:45], v197
	ds_read_b128 v[46:49], v197 offset:8704
	ds_read_b128 v[50:53], v197 offset:17408
	ds_read_b128 v[54:57], v197 offset:26112
	ds_read_b128 v[58:61], v197 offset:34816
	ds_read_b128 v[62:65], v197 offset:43520
	ds_read_b128 v[66:69], v197 offset:52224
	ds_read_b128 v[70:73], v197 offset:60928
	v_add_u32_e32 v40, s39, v189
	v_mad_i64_i32 v[40:41], s[12:13], v40, s7, v[38:39]
	s_lshl_b32 s48, s7, 5
	s_mov_b32 s49, 0
	s_waitcnt lgkmcnt(7)
	global_store_dwordx4 v[40:41], v[42:45], off
	v_lshl_add_u64 v[40:41], v[40:41], 0, s[48:49]
	s_waitcnt lgkmcnt(6)
	global_store_dwordx4 v[40:41], v[46:49], off
	v_lshl_add_u64 v[40:41], v[40:41], 0, s[48:49]
	s_waitcnt lgkmcnt(5)
	global_store_dwordx4 v[40:41], v[50:53], off
	v_lshl_add_u64 v[40:41], v[40:41], 0, s[48:49]
	s_waitcnt lgkmcnt(4)
	global_store_dwordx4 v[40:41], v[54:57], off
	v_lshl_add_u64 v[40:41], v[40:41], 0, s[48:49]
	s_waitcnt lgkmcnt(3)
	global_store_dwordx4 v[40:41], v[58:61], off
	v_lshl_add_u64 v[40:41], v[40:41], 0, s[48:49]
	s_waitcnt lgkmcnt(2)
	global_store_dwordx4 v[40:41], v[62:65], off
	v_lshl_add_u64 v[40:41], v[40:41], 0, s[48:49]
	s_waitcnt lgkmcnt(1)
	global_store_dwordx4 v[40:41], v[66:69], off
	v_lshl_add_u64 v[40:41], v[40:41], 0, s[48:49]
	s_waitcnt lgkmcnt(0)
	global_store_dwordx4 v[40:41], v[70:73], off
	s_mov_b64 s[12:13], -1
	s_barrier
	s_cbranch_vccz .LBB0_598
